# v28 + half-2 early K reads + K/rope-K base re-bias (12 fewer VALU per 2 tiles)
# baseline (speedup 1.0000x reference)
.LBB0_549:
	v_cndmask_b32_e64 v165, v165, v202, s[4:5]
	v_mul_f32_e32 v154, 0xbdd53b94, v165
	v_fmamk_f32 v202, v69, 0x3dd53b94, v154
	v_fmamk_f32 v215, v70, 0x3dd53b94, v154
	v_fmamk_f32 v232, v79, 0x3dd53b94, v154
	v_fmamk_f32 v233, v80, 0x3dd53b94, v154
	v_fmamk_f32 v155, v66, 0x3dd53b94, v154
	v_fmamk_f32 v156, v67, 0x3dd53b94, v154
	v_fmamk_f32 v157, v68, 0x3dd53b94, v154
	v_fmamk_f32 v216, v71, 0x3dd53b94, v154
	v_fmamk_f32 v217, v72, 0x3dd53b94, v154
	v_fmamk_f32 v218, v73, 0x3dd53b94, v154
	v_fmamk_f32 v219, v74, 0x3dd53b94, v154
	v_fmamk_f32 v220, v75, 0x3dd53b94, v154
	v_fmamk_f32 v221, v76, 0x3dd53b94, v154
	v_fmamk_f32 v222, v77, 0x3dd53b94, v154
	v_fmamk_f32 v223, v78, 0x3dd53b94, v154
	ds_read_b128 v[66:69], v174 offset:32768
	ds_read_b128 v[70:73], v174 offset:40960
	ds_read_b128 v[146:149], v176 offset:32768
	ds_read_b128 v[150:153], v176 offset:40960
	v_fmamk_f32 v82, v82, 0x3dd53b94, v154
	v_fmamk_f32 v83, v83, 0x3dd53b94, v154
	v_fmamk_f32 v84, v84, 0x3dd53b94, v154
	v_fmamk_f32 v85, v85, 0x3dd53b94, v154
	v_fmamk_f32 v86, v86, 0x3dd53b94, v154
	v_fmamk_f32 v87, v87, 0x3dd53b94, v154
	v_fmamk_f32 v88, v88, 0x3dd53b94, v154
	v_fmamk_f32 v89, v89, 0x3dd53b94, v154
	v_fmamk_f32 v90, v90, 0x3dd53b94, v154
	v_fmamk_f32 v91, v91, 0x3dd53b94, v154
	v_fmamk_f32 v92, v92, 0x3dd53b94, v154
	v_fmamk_f32 v93, v93, 0x3dd53b94, v154
	v_fmamk_f32 v94, v94, 0x3dd53b94, v154
	v_fmamk_f32 v95, v95, 0x3dd53b94, v154
	v_fmamk_f32 v96, v96, 0x3dd53b94, v154
	v_fmamk_f32 v97, v97, 0x3dd53b94, v154
	v_exp_f32_e32 v224, v82
	v_exp_f32_e32 v225, v83
	v_exp_f32_e32 v226, v84
	v_exp_f32_e32 v227, v85
	v_exp_f32_e32 v228, v86
	v_exp_f32_e32 v229, v87
	v_exp_f32_e32 v230, v88
	v_exp_f32_e32 v231, v89
	v_exp_f32_e32 v234, v90
	v_exp_f32_e32 v235, v91
	v_exp_f32_e32 v236, v92
	v_exp_f32_e32 v237, v93
	v_exp_f32_e32 v238, v94
	v_exp_f32_e32 v239, v95
	v_exp_f32_e32 v240, v96
	v_exp_f32_e32 v241, v97
	v_fmac_f32_e32 v154, 0x3dd53b94, v81
	v_exp_f32_e32 v155, v155
	v_exp_f32_e32 v156, v156
	s_waitcnt lgkmcnt(0)
	v_mfma_f32_32x32x16_bf16 v[82:97], v[66:69], v[142:145], 0
	v_exp_f32_e32 v157, v157
	v_exp_f32_e32 v202, v202
	v_exp_f32_e32 v215, v215
	v_exp_f32_e32 v216, v216
	v_exp_f32_e32 v217, v217
	v_exp_f32_e32 v218, v218
	v_exp_f32_e32 v219, v219
	v_mfma_f32_32x32x16_bf16 v[66:81], v[70:73], v[142:145], 0
	v_exp_f32_e32 v220, v220
	v_exp_f32_e32 v221, v221
	v_exp_f32_e32 v222, v222
	v_exp_f32_e32 v223, v223
	v_exp_f32_e32 v242, v232
	v_exp_f32_e32 v243, v233
	v_exp_f32_e32 v244, v154
	v_mfma_f32_32x32x16_bf16 v[82:97], v[146:149], v[138:141], v[82:97]
	v_mfma_f32_32x32x16_bf16 v[66:81], v[150:153], v[138:141], v[66:81]
	ds_read_b128 v[146:149], v178 offset:32768
	ds_read_b128 v[150:153], v178 offset:40960
	s_cmp_lg_u32 s98, 0
	s_cbranch_scc1 .Lattn_mla_nopf
	s_add_u32 s0, s38, s20
	s_addc_u32 s1, s39, s21
	s_add_u32 s100, s0, s42
	s_addc_u32 s101, s1, s43
	s_mov_b32 m0, s93
	v_lshl_add_u64 v[254:255], v[246:247], 0, s[100:101]
	global_load_lds_dwordx4 v[254:255], off
	s_add_u32 s100, s0, s46
	s_addc_u32 s101, s1, s47
	s_mov_b32 m0, s94
	v_lshl_add_u64 v[254:255], v[246:247], 0, s[100:101]
	global_load_lds_dwordx4 v[254:255], off
	s_add_u32 s100, s0, s44
	s_addc_u32 s101, s1, s45
	s_add_i32 s98, s89, s24
	s_mov_b32 m0, s98
	v_lshl_add_u64 v[254:255], v[248:249], 0, s[100:101]
	global_load_lds_dwordx4 v[254:255], off
	s_add_u32 s100, s0, s50
	s_addc_u32 s101, s1, s51
	s_add_i32 m0, s98, 0x2000
	v_lshl_add_u64 v[254:255], v[248:249], 0, s[100:101]
	global_load_lds_dwordx4 v[254:255], off
	s_add_u32 s0, s38, s88
	s_addc_u32 s1, s39, s87
	s_add_u32 s0, s0, s58
	s_addc_u32 s1, s1, s59
	s_mov_b32 m0, s95
	v_lshl_add_u64 v[254:255], v[250:251], 0, s[0:1]
	global_load_lds_dwordx4 v[254:255], off
